# attention fast path v2: next-tile staging under the QK MFMAs, first exp group under the second half of QK, register rotation + next loads under the last PV group
# baseline (speedup 1.0000x reference)
; __device__ __forceinline__ void unit(unsigned char* ws, LAS unsigned char* lds, int b, int h, int mp, int qb, const int tid_in) {
;     ...
;         for (int jt = 0; jt < 4; ++jt) { const bf16x8 kf0 = *(const LAS bf16x8*)(KS + (16 * jt + fr) * KP + 8 * fq), kf1 = *(const LAS bf16x8*)(KS + (16 * jt + fr) * KP + 32 + 8 * fq);
; #pragma unroll
;             for (int g = 0; g < 2; ++g) { const float nm = -m[g]; s[g][jt] = __builtin_amdgcn_mfma_f32_16x16x32_bf16(kf0, qf[g][0], (f32x4){nm, nm, nm, nm}, 0, 0, 0); s[g][jt] = __builtin_amdgcn_mfma_f32_16x16x32_bf16(kf1, qf[g][1], s[g][jt], 0, 0, 0); } }
;         const bool nearb = (qw0 - (k0 + 63) < 113);
;         bf16x8 pf[2][2];
; #pragma unroll
;         for (int g = 0; g < 2; ++g) {
;             if (nearb) {
;                 const LAS float* tb = TB + (256 + qw0 + 16 * g + fr - (k0 + 4 * fq));
; #pragma unroll
;                 for (int jt = 0; jt < 4; ++jt)
; #pragma unroll
;                     for (int jj = 0; jj < 4; ++jj) { const float bv = tb[-(16 * jt + jj)]; float x = s[g][jt][jj];
;                         asm("v_add_f32_e32 %0, %1, %2" : "=v"(x) : "v"(x), "v"(bv));
;                         s[g][jt][jj] = x; }
;             }
;             float mx = fmaxf(fmaxf(s[g][0][0], s[g][0][1]), fmaxf(s[g][0][2], s[g][0][3]));
; #pragma unroll
;             for (int jt = 1; jt < 4; ++jt) mx = fmaxf(mx, fmaxf(fmaxf(s[g][jt][0], s[g][jt][1]), fmaxf(s[g][jt][2], s[g][jt][3])));
;             if (__any(mx > 8.f)) {
;                 mx = fmaxf(mx, __shfl_xor(mx, 16)); mx = fmaxf(mx, __shfl_xor(mx, 32));
;                 const float dl = fmaxf(mx, 0.f), alpha = __builtin_amdgcn_exp2f(-dl);
;                 m[g] += dl; lacc[g] *= alpha;
; #pragma unroll
;                 for (int jt = 0; jt < 4; ++jt) s[g][jt] -= dl;
; #pragma unroll
;                 for (int et = 0; et < 8; ++et) o[g][et] *= alpha;
;             }
; #pragma unroll
;             for (int jt = 0; jt < 4; ++jt) {
; #pragma unroll
;                 for (int jj = 0; jj < 4; ++jj) s[g][jt][jj] = __builtin_amdgcn_exp2f(s[g][jt][jj]); }
; #pragma unroll
;             for (int sb = 0; sb < 2; ++sb) { u32x4 pw; pw.x = cvtpk(s[g][2 * sb][0], s[g][2 * sb][1]); pw.y = cvtpk(s[g][2 * sb][2], s[g][2 * sb][3]); pw.z = cvtpk(s[g][2 * sb + 1][0], s[g][2 * sb + 1][1]); pw.w = cvtpk(s[g][2 * sb + 1][2], s[g][2 * sb + 1][3]);
.Lattn_fast:
	s_bitcmp1_b32 s68, 0
	s_cselect_b32 s21, 0, 0x6c00
	v_add_u32_e32 v179, s21, v174
	v_lshl_add_u32 v178, v169, 1, v179
	ds_read_b128 v[222:225], v178
	ds_read_b128 v[226:229], v178 offset:64
	ds_read_b128 v[230:233], v178 offset:2304
	ds_read_b128 v[234:237], v178 offset:2368
	ds_read_b128 v[238:241], v178 offset:4608
	ds_read_b128 v[242:245], v178 offset:4672
	ds_read_b128 v[246:249], v178 offset:6912
	ds_read_b128 v[250:253], v178 offset:6976
	v_xor_b32_e32 v214, 0x80000000, v175
	v_mov_b32_e32 v215, v214
	v_mov_b32_e32 v216, v214
	v_mov_b32_e32 v217, v214
	v_xor_b32_e32 v218, 0x80000000, v177
	v_mov_b32_e32 v219, v218
	v_mov_b32_e32 v220, v218
	v_mov_b32_e32 v221, v218
	s_waitcnt lgkmcnt(7)
	v_mfma_f32_16x16x32_bf16 v[126:129], v[222:225], v[82:85], v[214:217]
	v_lshl_add_u32 v210, v168, 1, v179
	v_lshl_add_u32 v211, v167, 1, v179
	v_lshl_add_u32 v212, v166, 1, v179
	s_waitcnt lgkmcnt(6)
	v_mfma_f32_16x16x32_bf16 v[126:129], v[226:229], v[78:81], v[126:129]
	v_mov_b32_e32 v206, s20
	v_mov_b32_e32 v207, s20
	v_mov_b32_e32 v208, s20
	s_waitcnt lgkmcnt(5)
	v_mfma_f32_16x16x32_bf16 v[130:133], v[230:233], v[82:85], v[214:217]
	v_mov_b32_e32 v209, s20
	s_bitcmp1_b32 s68, 0
	s_cselect_b32 s23, 0x6c00, 0
	s_waitcnt lgkmcnt(4)
	v_mfma_f32_16x16x32_bf16 v[130:133], v[234:237], v[78:81], v[130:133]
	s_add_i32 s22, s23, 0
	v_add3_u32 v213, s22, v171, v0
	ds_write_b128 v213, v[110:113]
	s_waitcnt lgkmcnt(4)
	v_mfma_f32_16x16x32_bf16 v[138:141], v[238:241], v[82:85], v[214:217]
	v_and_b32_e32 v110, 0xffff, v102
	v_add3_u32 v111, s22, v170, v172
	v_lshrrev_b32_e32 v102, 16, v102
	s_waitcnt lgkmcnt(3)
	v_mfma_f32_16x16x32_bf16 v[138:141], v[242:245], v[78:81], v[138:141]
	v_lshl_or_b32 v110, v106, 16, v110
	v_and_or_b32 v102, v106, s33, v102
	v_add_u32_e32 v106, 0x2400, v111
	s_waitcnt lgkmcnt(2)
	v_mfma_f32_16x16x32_bf16 v[142:145], v[246:249], v[82:85], v[214:217]
	ds_write2_b32 v106, v110, v102 offset1:36
	v_and_b32_e32 v102, 0xffff, v103
	v_lshrrev_b32_e32 v103, 16, v103
	s_waitcnt lgkmcnt(2)
	v_mfma_f32_16x16x32_bf16 v[142:145], v[250:253], v[78:81], v[142:145]
	v_lshl_or_b32 v102, v107, 16, v102
	v_and_or_b32 v103, v107, s33, v103
	ds_write2_b32 v106, v102, v103 offset0:72 offset1:108
	v_mfma_f32_16x16x32_bf16 v[114:117], v[222:225], v[86:89], v[218:221]
	v_and_b32_e32 v102, 0xffff, v104
	v_lshrrev_b32_e32 v103, 16, v104
	v_lshl_or_b32 v102, v108, 16, v102
	v_mfma_f32_16x16x32_bf16 v[114:117], v[226:229], v[74:77], v[114:117]
	v_max3_f32 v181, v126, v127, v128
	v_and_or_b32 v103, v108, s33, v103
	ds_write2_b32 v106, v102, v103 offset0:144 offset1:180
	v_mfma_f32_16x16x32_bf16 v[118:121], v[230:233], v[86:89], v[218:221]
	v_max3_f32 v182, v129, v130, v131
	v_and_b32_e32 v102, 0xffff, v105
	v_lshrrev_b32_e32 v103, 16, v105
	v_mfma_f32_16x16x32_bf16 v[118:121], v[234:237], v[74:77], v[118:121]
	v_max3_f32 v181, v132, v133, v181
	v_max3_f32 v183, v138, v139, v140
	v_max3_f32 v181, v141, v182, v181
	v_lshl_or_b32 v102, v109, 16, v102
	v_and_or_b32 v103, v109, s33, v103
	ds_write2_b32 v106, v102, v103 offset0:216 offset1:252
	v_max3_f32 v182, v142, v143, v144
	v_max3_f32 v181, v145, v183, v181
	v_max_f32_e32 v180, v182, v181
	v_cmp_lt_f32_e32 vcc, s94, v180
	s_cbranch_vccnz .Lattn_rare0
.Lattn_back0:
	ds_read_b128 v[222:225], v178 offset:9216
	ds_read_b128 v[226:229], v178 offset:11536
	ds_read_b128 v[230:233], v178 offset:13856
	ds_read_b128 v[234:237], v178 offset:16176
	v_mfma_f32_16x16x32_bf16 v[122:125], v[238:241], v[86:89], v[218:221]
	v_exp_f32_e32 v126, v126
	v_exp_f32_e32 v127, v127
	v_mfma_f32_16x16x32_bf16 v[122:125], v[242:245], v[74:77], v[122:125]
	v_exp_f32_e32 v128, v128
	v_exp_f32_e32 v129, v129
	ds_read_b128 v[238:241], v178 offset:18496
	ds_read_b128 v[242:245], v210 offset:20736
	v_mfma_f32_16x16x32_bf16 v[134:137], v[246:249], v[86:89], v[218:221]
	v_exp_f32_e32 v130, v130
	v_exp_f32_e32 v131, v131
	v_mfma_f32_16x16x32_bf16 v[134:137], v[250:253], v[74:77], v[134:137]
	v_exp_f32_e32 v132, v132
	v_exp_f32_e32 v133, v133
	ds_read_b128 v[246:249], v211 offset:23040
	ds_read_b128 v[250:253], v212 offset:25344
	v_cvt_pk_bf16_f32 v126, v126, v127
	v_cvt_pk_bf16_f32 v127, v128, v129
	v_cvt_pk_bf16_f32 v128, v130, v131
	v_cvt_pk_bf16_f32 v129, v132, v133
	s_nop 1
	v_mfma_f32_16x16x32_bf16 v[70:73], v[206:209], v[126:129], v[70:73]
	v_max3_f32 v181, v114, v115, v116
	v_max3_f32 v182, v117, v118, v119
	v_max3_f32 v181, v120, v121, v181
	s_waitcnt lgkmcnt(7)
	v_mfma_f32_16x16x32_bf16 v[66:69], v[222:225], v[126:129], v[66:69]
	v_max3_f32 v183, v122, v123, v124
	v_max3_f32 v181, v125, v182, v181
	v_max3_f32 v182, v134, v135, v136
	s_waitcnt lgkmcnt(6)
	v_mfma_f32_16x16x32_bf16 v[62:65], v[226:229], v[126:129], v[62:65]
	v_max3_f32 v181, v137, v183, v181
	v_max_f32_e32 v180, v182, v181
	v_cmp_lt_f32_e32 vcc, s94, v180
	s_cbranch_vccnz .Lattn_rare1
; #define LAS __attribute__((address_space(3)))
; __device__ __forceinline__ void unit(unsigned char* ws, LAS unsigned char* lds, int b, int h, int mp, int qb, const int tid_in) {
;     ...
;         for (int g = 0; g < 2; ++g) {
;             lacc[g] = __builtin_amdgcn_mfma_f32_16x16x32_bf16(onesf, pf[g][0], lacc[g], 0, 0, 0); lacc[g] = __builtin_amdgcn_mfma_f32_16x16x32_bf16(onesf, pf[g][1], lacc[g], 0, 0, 0); }
; #pragma unroll
;         for (int et = 0; et < 8; ++et) { const LAS bf16_t* vrow = VT + (16 * et + fr) * KP;
;             const bf16x8 vf0 = *(const LAS bf16x8*)(vrow + ((8 * fq + 8 * et) & 63)), vf1 = *(const LAS bf16x8*)(vrow + ((32 + 8 * fq + 8 * et) & 63));
; #pragma unroll
;             for (int g = 0; g < 2; ++g) { o[g][et] = __builtin_amdgcn_mfma_f32_16x16x32_bf16(vf0, pf[g][0], o[g][et], 0, 0, 0); o[g][et] = __builtin_amdgcn_mfma_f32_16x16x32_bf16(vf1, pf[g][1], o[g][et], 0, 0, 0); } }
;         }
;         if (kt + 1 < NT) { FA3_STAGE((kt + 1) & 1); kA = kB; vA0 = vB0; vA1 = vB1;
;             if (kt + 3 < NT) { const size_t off = (size_t)(kt + 3) * 64 * 512; kB = *(const u32x4*)(kg + off); vB0 = *(const u32x4*)(vg + off); vB1 = *(const u32x4*)(vg + off + 512); } }
.Lattn_back1:
	s_waitcnt lgkmcnt(5)
	v_mfma_f32_16x16x32_bf16 v[58:61], v[230:233], v[126:129], v[58:61]
	v_exp_f32_e32 v114, v114
	v_exp_f32_e32 v115, v115
	s_waitcnt lgkmcnt(4)
	v_mfma_f32_16x16x32_bf16 v[54:57], v[234:237], v[126:129], v[54:57]
	v_exp_f32_e32 v116, v116
	v_exp_f32_e32 v117, v117
	s_waitcnt lgkmcnt(3)
	v_mfma_f32_16x16x32_bf16 v[50:53], v[238:241], v[126:129], v[50:53]
	v_exp_f32_e32 v118, v118
	v_exp_f32_e32 v119, v119
	v_cvt_pk_bf16_f32 v114, v114, v115
	s_waitcnt lgkmcnt(2)
	v_mfma_f32_16x16x32_bf16 v[46:49], v[242:245], v[126:129], v[46:49]
	v_exp_f32_e32 v120, v120
	v_exp_f32_e32 v121, v121
	v_cvt_pk_bf16_f32 v115, v116, v117
	s_waitcnt lgkmcnt(1)
	v_mfma_f32_16x16x32_bf16 v[42:45], v[246:249], v[126:129], v[42:45]
	v_cvt_pk_bf16_f32 v116, v118, v119
	s_waitcnt lgkmcnt(0)
	v_mfma_f32_16x16x32_bf16 v[34:37], v[250:253], v[126:129], v[34:37]
	v_cvt_pk_bf16_f32 v117, v120, v121
	s_nop 1
	v_mfma_f32_16x16x32_bf16 v[38:41], v[206:209], v[114:117], v[38:41]
	v_exp_f32_e32 v138, v138
	v_mfma_f32_16x16x32_bf16 v[30:33], v[222:225], v[114:117], v[30:33]
	ds_read_b128 v[222:225], v178 offset:9280
	v_exp_f32_e32 v139, v139
	v_mfma_f32_16x16x32_bf16 v[26:29], v[226:229], v[114:117], v[26:29]
	ds_read_b128 v[226:229], v210 offset:11520
	v_exp_f32_e32 v140, v140
	v_mfma_f32_16x16x32_bf16 v[22:25], v[230:233], v[114:117], v[22:25]
	ds_read_b128 v[230:233], v211 offset:13824
	v_exp_f32_e32 v141, v141
	v_mfma_f32_16x16x32_bf16 v[10:13], v[234:237], v[114:117], v[10:13]
	ds_read_b128 v[234:237], v212 offset:16128
	v_exp_f32_e32 v142, v142
	v_mfma_f32_16x16x32_bf16 v[18:21], v[238:241], v[114:117], v[18:21]
	ds_read_b128 v[238:241], v178 offset:18432
	v_exp_f32_e32 v143, v143
	v_cvt_pk_bf16_f32 v130, v138, v139
	v_mfma_f32_16x16x32_bf16 v[14:17], v[242:245], v[114:117], v[14:17]
	ds_read_b128 v[242:245], v178 offset:20752
	v_exp_f32_e32 v144, v144
	v_cvt_pk_bf16_f32 v131, v140, v141
	v_mfma_f32_16x16x32_bf16 v[6:9], v[246:249], v[114:117], v[6:9]
	ds_read_b128 v[246:249], v178 offset:23072
	v_exp_f32_e32 v145, v145
	v_cvt_pk_bf16_f32 v132, v142, v143
	v_mfma_f32_16x16x32_bf16 v[2:5], v[250:253], v[114:117], v[2:5]
	ds_read_b128 v[250:253], v178 offset:25392
	v_cvt_pk_bf16_f32 v133, v144, v145
	s_nop 1
	v_mfma_f32_16x16x32_bf16 v[70:73], v[206:209], v[130:133], v[70:73]
	v_exp_f32_e32 v122, v122
	s_waitcnt lgkmcnt(7)
	v_mfma_f32_16x16x32_bf16 v[66:69], v[222:225], v[130:133], v[66:69]
	v_exp_f32_e32 v123, v123
	s_waitcnt lgkmcnt(6)
	v_mfma_f32_16x16x32_bf16 v[62:65], v[226:229], v[130:133], v[62:65]
	v_exp_f32_e32 v124, v124
	s_waitcnt lgkmcnt(5)
	v_mfma_f32_16x16x32_bf16 v[58:61], v[230:233], v[130:133], v[58:61]
	v_exp_f32_e32 v125, v125
	s_waitcnt lgkmcnt(4)
	v_mfma_f32_16x16x32_bf16 v[54:57], v[234:237], v[130:133], v[54:57]
	v_exp_f32_e32 v134, v134
	s_waitcnt lgkmcnt(3)
	v_mfma_f32_16x16x32_bf16 v[50:53], v[238:241], v[130:133], v[50:53]
	v_exp_f32_e32 v135, v135
	v_cvt_pk_bf16_f32 v118, v122, v123
	s_waitcnt lgkmcnt(2)
	v_mfma_f32_16x16x32_bf16 v[46:49], v[242:245], v[130:133], v[46:49]
	v_exp_f32_e32 v136, v136
	v_cvt_pk_bf16_f32 v119, v124, v125
	s_waitcnt lgkmcnt(1)
	v_mfma_f32_16x16x32_bf16 v[42:45], v[246:249], v[130:133], v[42:45]
	v_exp_f32_e32 v137, v137
	v_cvt_pk_bf16_f32 v120, v134, v135
	s_waitcnt lgkmcnt(0)
	v_mfma_f32_16x16x32_bf16 v[34:37], v[250:253], v[130:133], v[34:37]
	v_cvt_pk_bf16_f32 v121, v136, v137
	s_nop 1
	v_mfma_f32_16x16x32_bf16 v[38:41], v[206:209], v[118:121], v[38:41]
	v_mfma_f32_16x16x32_bf16 v[30:33], v[222:225], v[118:121], v[30:33]
	s_waitcnt vmcnt(0)
	v_mov_b64_e32 v[110:111], v[90:91]
	v_mov_b64_e32 v[112:113], v[92:93]
	v_mov_b64_e32 v[102:103], v[94:95]
	v_mfma_f32_16x16x32_bf16 v[26:29], v[226:229], v[118:121], v[26:29]
	v_mov_b64_e32 v[104:105], v[96:97]
	v_mov_b64_e32 v[106:107], v[98:99]
	v_mov_b64_e32 v[108:109], v[100:101]
	v_mfma_f32_16x16x32_bf16 v[22:25], v[230:233], v[118:121], v[22:25]
	s_cmp_ge_u32 s68, s70
	s_cbranch_scc1 .Lattn_nold
	v_lshl_add_u64 v[114:115], v[160:161], 0, s[14:15]
	v_add_co_u32_e32 v114, vcc, 0xa630000, v114
	v_lshl_add_u64 v[116:117], v[162:163], 0, s[14:15]
	s_nop 0
	v_addc_co_u32_e32 v115, vcc, 0, v115, vcc
	global_load_dwordx4 v[90:93], v[116:117], off
	global_load_dwordx4 v[94:97], v[114:115], off
	global_load_dwordx4 v[98:101], v[114:115], off offset:1024
.Lattn_nold:
	v_mfma_f32_16x16x32_bf16 v[10:13], v[234:237], v[118:121], v[10:13]
	v_mfma_f32_16x16x32_bf16 v[18:21], v[238:241], v[118:121], v[18:21]
	v_mfma_f32_16x16x32_bf16 v[14:17], v[242:245], v[118:121], v[14:17]
	v_mfma_f32_16x16x32_bf16 v[6:9], v[246:249], v[118:121], v[6:9]
	v_mfma_f32_16x16x32_bf16 v[2:5], v[250:253], v[118:121], v[2:5]
	s_branch .LBB0_198
